# in-projection epilogue: V^T written as 8-byte runs after an in-quad 4x4 transpose (DPP + v_perm) instead of four 2-byte stores per lane
# baseline (speedup 1.0000x reference)
.LBB0_374:
.LBB0_375:
	s_cmp_lt_i32 s14, 5
	s_cselect_b64 s[0:1], -1, 0
	s_cmp_gt_i32 s15, 4
	s_cselect_b64 s[4:5], -1, 0
	s_and_b64 s[0:1], s[0:1], s[4:5]
	s_andn2_b64 vcc, exec, s[0:1]
	s_cbranch_vccnz .LBB0_1142
	s_waitcnt vmcnt(0)
	v_and_b32_e32 v245, 3, v0
	v_mul_u32_u24_e32 v245, 0x7e, v245
	v_and_b32_e32 v249, 1, v0
	v_cmp_eq_u32_e32 vcc, 1, v249
	v_mov_b32_e32 v248, 0x5040100
	v_mov_b32_e32 v249, 0x3020706
	s_nop 1
	v_cndmask_b32_e32 v248, v248, v249, vcc
	v_and_b32_e32 v249, 2, v0
	v_cmp_ne_u32_e64 s[98:99], 0, v249
	v_mov_b32_e32 v10, v0
	s_cmpk_lt_i32 s2, 0x50a
	s_cselect_b64 s[0:1], -1, 0
	s_cmpk_gt_i32 s2, 0x509
	v_readfirstlane_b32 s6, v10
	s_cbranch_scc1 .LBB0_382
	s_ashr_i32 s3, s2, 31
	s_lshr_b32 s3, s3, 29
	s_add_i32 s3, s2, s3
	s_and_b32 s4, s3, -8
	s_sub_i32 s7, s2, s4
	s_cmp_gt_i32 s7, 1
	s_cbranch_scc0 .LBB0_379
	s_mul_i32 s4, s7, 0xa1
	s_add_i32 s8, s4, 2
	s_cbranch_execz .LBB0_380
	s_branch .LBB0_381

.LBB0_404:
	s_and_b64 vcc, exec, s[12:13]
	s_cbranch_vccz .LBB0_406
	s_and_b64 s[12:13], s[8:9], exec
	s_cselect_b32 s12, s89, 0xc100000
	v_mov_b32_e32 v134, s93
	s_add_u32 s12, s84, s12
	v_cndmask_b32_e64 v171, v167, v165, s[8:9]
	v_cndmask_b32_e64 v170, v166, v164, s[8:9]
	v_cndmask_b32_e64 v183, v134, v175, s[8:9]
	v_mov_b32_e32 v134, s71
	s_addc_u32 s13, s85, 0
	v_cndmask_b32_e64 v178, v134, v174, s[8:9]
	v_lshl_add_u64 v[170:171], s[12:13], 0, v[170:171]
	v_lshlrev_b32_e32 v134, 2, v177
	v_lshl_add_u64 v[170:171], v[170:171], 0, v[134:135]
	s_and_b64 s[12:13], s[8:9], exec
	v_or_b32_e32 v182, v178, v136
	global_store_dwordx4 v[170:171], v[126:129], off nt
	s_cselect_b32 s13, s28, s57
	s_cselect_b32 s12, s3, s56
	v_lshlrev_b64 v[170:171], 7, v[182:183]
	v_lshl_add_u64 v[170:171], s[12:13], 0, v[170:171]
	v_lshl_add_u32 v134, v138, 1, v245
	v_lshl_add_u64 v[170:171], v[170:171], 0, v[134:135]
	v_cvt_pk_bf16_f32 v134, v126, v127
	v_cvt_pk_bf16_f32 v178, v128, v129
	s_nop 1
	v_mov_b32_dpp v246, v134 quad_perm:[1,0,3,2] row_mask:0xf bank_mask:0xf
	v_mov_b32_dpp v247, v178 quad_perm:[1,0,3,2] row_mask:0xf bank_mask:0xf
	v_perm_b32 v246, v246, v134, v248
	v_perm_b32 v247, v247, v178, v248
	s_nop 1
	v_mov_b32_dpp v250, v246 quad_perm:[2,3,0,1] row_mask:0xf bank_mask:0xf
	v_mov_b32_dpp v251, v247 quad_perm:[2,3,0,1] row_mask:0xf bank_mask:0xf
	v_cndmask_b32_e64 v252, v246, v251, s[98:99]
	v_cndmask_b32_e64 v253, v250, v247, s[98:99]
	global_store_dwordx2 v[170:171], v[252:253], off

.LBB0_425:
	s_and_b64 vcc, exec, s[12:13]
	s_cbranch_vccz .LBB0_427
	s_and_b64 s[12:13], s[8:9], exec
	s_cselect_b32 s12, s89, 0xc100000
	v_mov_b32_e32 v128, s93
	s_add_u32 s12, s84, s12
	v_cndmask_b32_e64 v127, v167, v165, s[8:9]
	v_cndmask_b32_e64 v126, v166, v164, s[8:9]
	v_cndmask_b32_e64 v129, v128, v175, s[8:9]
	v_mov_b32_e32 v128, s71
	s_addc_u32 s13, s85, 0
	v_cndmask_b32_e64 v128, v128, v174, s[8:9]
	v_lshl_add_u64 v[126:127], s[12:13], 0, v[126:127]
	v_lshlrev_b32_e32 v174, 2, v177
	v_mov_b32_e32 v175, v135
	v_lshl_add_u64 v[126:127], v[126:127], 0, v[174:175]
	s_and_b64 s[12:13], s[8:9], exec
	v_and_or_b32 v128, v178, s94, v128
	global_store_dwordx4 v[126:127], v[122:125], off offset:64 nt
	s_cselect_b32 s13, s28, s57
	s_cselect_b32 s12, s3, s56
	v_lshlrev_b64 v[126:127], 7, v[128:129]
	v_lshl_add_u64 v[126:127], s[12:13], 0, v[126:127]
	v_lshl_add_u32 v128, v138, 1, v245
	v_mov_b32_e32 v129, v135
	v_lshl_add_u64 v[126:127], v[126:127], 0, v[128:129]
	v_cvt_pk_bf16_f32 v128, v122, v123
	v_cvt_pk_bf16_f32 v129, v124, v125
	s_nop 1
	v_mov_b32_dpp v246, v128 quad_perm:[1,0,3,2] row_mask:0xf bank_mask:0xf
	v_mov_b32_dpp v247, v129 quad_perm:[1,0,3,2] row_mask:0xf bank_mask:0xf
	v_perm_b32 v246, v246, v128, v248
	v_perm_b32 v247, v247, v129, v248
	s_nop 1
	v_mov_b32_dpp v250, v246 quad_perm:[2,3,0,1] row_mask:0xf bank_mask:0xf
	v_mov_b32_dpp v251, v247 quad_perm:[2,3,0,1] row_mask:0xf bank_mask:0xf
	v_cndmask_b32_e64 v252, v246, v251, s[98:99]
	v_cndmask_b32_e64 v253, v250, v247, s[98:99]
	global_store_dwordx2 v[126:127], v[252:253], off

.LBB0_446:
	s_and_b64 vcc, exec, s[12:13]
	s_cbranch_vccz .LBB0_448
	s_and_b64 s[12:13], s[8:9], exec
	s_cselect_b32 s12, s89, 0xc100000
	s_add_u32 s12, s84, s12
	v_cndmask_b32_e64 v173, v167, v165, s[8:9]
	v_cndmask_b32_e64 v172, v166, v164, s[8:9]
	s_addc_u32 s13, s85, 0
	v_cndmask_b32_e64 v124, v175, v128, s[8:9]
	v_lshl_add_u64 v[172:173], s[12:13], 0, v[172:173]
	v_lshlrev_b32_e32 v182, 2, v177
	v_mov_b32_e32 v183, v135
	v_cndmask_b32_e64 v181, v125, v129, s[8:9]
	v_lshl_add_u64 v[172:173], v[172:173], 0, v[182:183]
	s_and_b64 s[12:13], s[8:9], exec
	v_or_b32_e32 v180, v124, v136
	global_store_dwordx4 v[172:173], v[118:121], off offset:512 nt
	s_cselect_b32 s13, s28, s57
	s_cselect_b32 s12, s3, s56
	v_lshlrev_b64 v[172:173], 7, v[180:181]
	v_lshl_add_u64 v[172:173], s[12:13], 0, v[172:173]
	v_lshl_add_u32 v180, v138, 1, v245
	v_mov_b32_e32 v181, v135
	v_lshl_add_u64 v[172:173], v[172:173], 0, v[180:181]
	v_cvt_pk_bf16_f32 v124, v118, v119
	v_cvt_pk_bf16_f32 v180, v120, v121
	s_nop 1
	v_mov_b32_dpp v246, v124 quad_perm:[1,0,3,2] row_mask:0xf bank_mask:0xf
	v_mov_b32_dpp v247, v180 quad_perm:[1,0,3,2] row_mask:0xf bank_mask:0xf
	v_perm_b32 v246, v246, v124, v248
	v_perm_b32 v247, v247, v180, v248
	s_nop 1
	v_mov_b32_dpp v250, v246 quad_perm:[2,3,0,1] row_mask:0xf bank_mask:0xf
	v_mov_b32_dpp v251, v247 quad_perm:[2,3,0,1] row_mask:0xf bank_mask:0xf
	v_cndmask_b32_e64 v252, v246, v251, s[98:99]
	v_cndmask_b32_e64 v253, v250, v247, s[98:99]
	global_store_dwordx2 v[172:173], v[252:253], off

.LBB0_461:
	s_and_b64 vcc, exec, s[12:13]
	s_cbranch_vccz .LBB0_463
	s_and_b64 s[12:13], s[8:9], exec
	s_cselect_b32 s12, s89, 0xc100000
	v_mov_b32_e32 v166, s93
	s_add_u32 s12, s84, s12
	v_cndmask_b32_e64 v121, v117, v115, s[8:9]
	v_cndmask_b32_e64 v120, v116, v114, s[8:9]
	v_cndmask_b32_e64 v167, v166, v129, s[8:9]
	v_mov_b32_e32 v166, s71
	s_addc_u32 s13, s85, 0
	v_cndmask_b32_e64 v166, v166, v128, s[8:9]
	v_lshl_add_u64 v[120:121], s[12:13], 0, v[120:121]
	v_lshlrev_b32_e32 v168, 2, v177
	v_mov_b32_e32 v169, v135
	v_lshl_add_u64 v[120:121], v[120:121], 0, v[168:169]
	s_and_b64 s[12:13], s[8:9], exec
	v_or_b32_e32 v166, v166, v136
	global_store_dwordx4 v[120:121], v[110:113], off nt
	s_cselect_b32 s13, s28, s57
	s_cselect_b32 s12, s3, s56
	v_lshlrev_b64 v[120:121], 7, v[166:167]
	v_lshl_add_u64 v[120:121], s[12:13], 0, v[120:121]
	v_lshl_add_u32 v166, v142, 1, v245
	v_mov_b32_e32 v167, v135
	v_lshl_add_u64 v[120:121], v[120:121], 0, v[166:167]
	v_cvt_pk_bf16_f32 v166, v110, v111
	v_cvt_pk_bf16_f32 v167, v112, v113
	s_nop 1
	v_mov_b32_dpp v246, v166 quad_perm:[1,0,3,2] row_mask:0xf bank_mask:0xf
	v_mov_b32_dpp v247, v167 quad_perm:[1,0,3,2] row_mask:0xf bank_mask:0xf
	v_perm_b32 v246, v246, v166, v248
	v_perm_b32 v247, v247, v167, v248
	s_nop 1
	v_mov_b32_dpp v250, v246 quad_perm:[2,3,0,1] row_mask:0xf bank_mask:0xf
	v_mov_b32_dpp v251, v247 quad_perm:[2,3,0,1] row_mask:0xf bank_mask:0xf
	v_cndmask_b32_e64 v252, v246, v251, s[98:99]
	v_cndmask_b32_e64 v253, v250, v247, s[98:99]
	global_store_dwordx2 v[120:121], v[252:253], off

.LBB0_476:
	s_and_b64 vcc, exec, s[12:13]
	s_cbranch_vccz .LBB0_478
	s_and_b64 s[12:13], s[8:9], exec
	s_cselect_b32 s12, s89, 0xc100000
	s_add_u32 s12, s84, s12
	v_cndmask_b32_e64 v111, v117, v115, s[8:9]
	v_cndmask_b32_e64 v110, v116, v114, s[8:9]
	s_addc_u32 s13, s85, 0
	v_cndmask_b32_e64 v112, v175, v108, s[8:9]
	v_lshl_add_u64 v[110:111], s[12:13], 0, v[110:111]
	v_lshlrev_b32_e32 v126, 2, v177
	v_mov_b32_e32 v127, v135
	v_cndmask_b32_e64 v113, v125, v109, s[8:9]
	v_lshl_add_u64 v[110:111], v[110:111], 0, v[126:127]
	s_and_b64 s[12:13], s[8:9], exec
	v_or_b32_e32 v112, v112, v136
	global_store_dwordx4 v[110:111], v[102:105], off offset:512 nt
	s_cselect_b32 s13, s28, s57
	s_cselect_b32 s12, s3, s56
	v_lshlrev_b64 v[110:111], 7, v[112:113]
	v_lshl_add_u64 v[110:111], s[12:13], 0, v[110:111]
	v_lshl_add_u32 v112, v142, 1, v245
	v_mov_b32_e32 v113, v135
	v_lshl_add_u64 v[110:111], v[110:111], 0, v[112:113]
	v_cvt_pk_bf16_f32 v112, v102, v103
	v_cvt_pk_bf16_f32 v113, v104, v105
	s_nop 1
	v_mov_b32_dpp v246, v112 quad_perm:[1,0,3,2] row_mask:0xf bank_mask:0xf
	v_mov_b32_dpp v247, v113 quad_perm:[1,0,3,2] row_mask:0xf bank_mask:0xf
	v_perm_b32 v246, v246, v112, v248
	v_perm_b32 v247, v247, v113, v248
	s_nop 1
	v_mov_b32_dpp v250, v246 quad_perm:[2,3,0,1] row_mask:0xf bank_mask:0xf
	v_mov_b32_dpp v251, v247 quad_perm:[2,3,0,1] row_mask:0xf bank_mask:0xf
	v_cndmask_b32_e64 v252, v246, v251, s[98:99]
	v_cndmask_b32_e64 v253, v250, v247, s[98:99]
	global_store_dwordx2 v[110:111], v[252:253], off

.LBB0_491:
	s_and_b64 vcc, exec, s[12:13]
	s_cbranch_vccz .LBB0_493
	s_and_b64 s[12:13], s[8:9], exec
	s_cselect_b32 s12, s89, 0xc100000
	v_mov_b32_e32 v112, s93
	s_add_u32 s12, s84, s12
	v_cndmask_b32_e64 v105, v101, v99, s[8:9]
	v_cndmask_b32_e64 v104, v100, v98, s[8:9]
	v_cndmask_b32_e64 v113, v112, v109, s[8:9]
	v_mov_b32_e32 v112, s71
	s_addc_u32 s13, s85, 0
	v_cndmask_b32_e64 v112, v112, v108, s[8:9]
	v_lshl_add_u64 v[104:105], s[12:13], 0, v[104:105]
	v_lshlrev_b32_e32 v114, 2, v177
	v_mov_b32_e32 v115, v135
	v_lshl_add_u64 v[104:105], v[104:105], 0, v[114:115]
	s_and_b64 s[12:13], s[8:9], exec
	v_or_b32_e32 v112, v112, v136
	global_store_dwordx4 v[104:105], v[94:97], off nt
	s_cselect_b32 s13, s28, s57
	s_cselect_b32 s12, s3, s56
	v_lshlrev_b64 v[104:105], 7, v[112:113]
	v_cndmask_b32_e64 v112, v146, v138, s[8:9]
	v_lshl_add_u64 v[104:105], s[12:13], 0, v[104:105]
	v_lshl_add_u32 v112, v112, 1, v245
	v_mov_b32_e32 v113, v135
	v_lshl_add_u64 v[104:105], v[104:105], 0, v[112:113]
	v_cvt_pk_bf16_f32 v112, v94, v95
	v_cvt_pk_bf16_f32 v113, v96, v97
	s_nop 1
	v_mov_b32_dpp v246, v112 quad_perm:[1,0,3,2] row_mask:0xf bank_mask:0xf
	v_mov_b32_dpp v247, v113 quad_perm:[1,0,3,2] row_mask:0xf bank_mask:0xf
	v_perm_b32 v246, v246, v112, v248
	v_perm_b32 v247, v247, v113, v248
	s_nop 1
	v_mov_b32_dpp v250, v246 quad_perm:[2,3,0,1] row_mask:0xf bank_mask:0xf
	v_mov_b32_dpp v251, v247 quad_perm:[2,3,0,1] row_mask:0xf bank_mask:0xf
	v_cndmask_b32_e64 v252, v246, v251, s[98:99]
	v_cndmask_b32_e64 v253, v250, v247, s[98:99]
	global_store_dwordx2 v[104:105], v[252:253], off

.LBB0_506:
	s_and_b64 vcc, exec, s[12:13]
	s_cbranch_vccz .LBB0_508
	s_and_b64 s[12:13], s[8:9], exec
	s_cselect_b32 s12, s89, 0xc100000
	s_add_u32 s12, s84, s12
	v_cndmask_b32_e64 v95, v101, v99, s[8:9]
	v_cndmask_b32_e64 v94, v100, v98, s[8:9]
	s_addc_u32 s13, s85, 0
	v_cndmask_b32_e64 v96, v175, v92, s[8:9]
	v_lshl_add_u64 v[94:95], s[12:13], 0, v[94:95]
	v_lshlrev_b32_e32 v106, 2, v177
	v_mov_b32_e32 v107, v135
	v_cndmask_b32_e64 v97, v125, v93, s[8:9]
	v_lshl_add_u64 v[94:95], v[94:95], 0, v[106:107]
	s_and_b64 s[12:13], s[8:9], exec
	v_or_b32_e32 v96, v96, v136
	global_store_dwordx4 v[94:95], v[86:89], off offset:512 nt
	s_cselect_b32 s13, s28, s57
	s_cselect_b32 s12, s3, s56
	v_lshlrev_b64 v[94:95], 7, v[96:97]
	v_cndmask_b32_e64 v96, v146, v138, s[8:9]
	v_lshl_add_u64 v[94:95], s[12:13], 0, v[94:95]
	v_lshl_add_u32 v96, v96, 1, v245
	v_mov_b32_e32 v97, v135
	v_lshl_add_u64 v[94:95], v[94:95], 0, v[96:97]
	v_cvt_pk_bf16_f32 v96, v86, v87
	v_cvt_pk_bf16_f32 v97, v88, v89
	s_nop 1
	v_mov_b32_dpp v246, v96 quad_perm:[1,0,3,2] row_mask:0xf bank_mask:0xf
	v_mov_b32_dpp v247, v97 quad_perm:[1,0,3,2] row_mask:0xf bank_mask:0xf
	v_perm_b32 v246, v246, v96, v248
	v_perm_b32 v247, v247, v97, v248
	s_nop 1
	v_mov_b32_dpp v250, v246 quad_perm:[2,3,0,1] row_mask:0xf bank_mask:0xf
	v_mov_b32_dpp v251, v247 quad_perm:[2,3,0,1] row_mask:0xf bank_mask:0xf
	v_cndmask_b32_e64 v252, v246, v251, s[98:99]
	v_cndmask_b32_e64 v253, v250, v247, s[98:99]
	global_store_dwordx2 v[94:95], v[252:253], off

.LBB0_521:
	s_and_b64 vcc, exec, s[12:13]
	s_cbranch_vccz .LBB0_523
	s_and_b64 s[12:13], s[8:9], exec
	s_cselect_b32 s12, s89, 0xc100000
	v_mov_b32_e32 v96, s93
	s_add_u32 s12, s84, s12
	v_cndmask_b32_e64 v89, v85, v83, s[8:9]
	v_cndmask_b32_e64 v88, v84, v82, s[8:9]
	v_cndmask_b32_e64 v97, v96, v93, s[8:9]
	v_mov_b32_e32 v96, s71
	s_addc_u32 s13, s85, 0
	v_cndmask_b32_e64 v96, v96, v92, s[8:9]
	v_lshl_add_u64 v[88:89], s[12:13], 0, v[88:89]
	v_lshlrev_b32_e32 v98, 2, v177
	v_mov_b32_e32 v99, v135
	v_lshl_add_u64 v[88:89], v[88:89], 0, v[98:99]
	s_and_b64 s[12:13], s[8:9], exec
	v_or_b32_e32 v96, v96, v136
	global_store_dwordx4 v[88:89], v[78:81], off nt
	s_cselect_b32 s13, s28, s57
	s_cselect_b32 s12, s3, s56
	v_lshlrev_b64 v[88:89], 7, v[96:97]
	v_cndmask_b32_e64 v96, v148, v150, s[8:9]
	v_lshl_add_u64 v[88:89], s[12:13], 0, v[88:89]
	v_lshl_add_u32 v96, v96, 1, v245
	v_mov_b32_e32 v97, v135
	v_lshl_add_u64 v[88:89], v[88:89], 0, v[96:97]
	v_cvt_pk_bf16_f32 v96, v78, v79
	v_cvt_pk_bf16_f32 v97, v80, v81
	s_nop 1
	v_mov_b32_dpp v246, v96 quad_perm:[1,0,3,2] row_mask:0xf bank_mask:0xf
	v_mov_b32_dpp v247, v97 quad_perm:[1,0,3,2] row_mask:0xf bank_mask:0xf
	v_perm_b32 v246, v246, v96, v248
	v_perm_b32 v247, v247, v97, v248
	s_nop 1
	v_mov_b32_dpp v250, v246 quad_perm:[2,3,0,1] row_mask:0xf bank_mask:0xf
	v_mov_b32_dpp v251, v247 quad_perm:[2,3,0,1] row_mask:0xf bank_mask:0xf
	v_cndmask_b32_e64 v252, v246, v251, s[98:99]
	v_cndmask_b32_e64 v253, v250, v247, s[98:99]
	global_store_dwordx2 v[88:89], v[252:253], off

.LBB0_536:
	s_and_b64 vcc, exec, s[12:13]
	s_cbranch_vccz .LBB0_538
	s_and_b64 s[12:13], s[8:9], exec
	s_cselect_b32 s12, s89, 0xc100000
	s_add_u32 s12, s84, s12
	v_cndmask_b32_e64 v79, v85, v83, s[8:9]
	v_cndmask_b32_e64 v78, v84, v82, s[8:9]
	s_addc_u32 s13, s85, 0
	v_cndmask_b32_e64 v80, v175, v76, s[8:9]
	v_lshl_add_u64 v[78:79], s[12:13], 0, v[78:79]
	v_lshlrev_b32_e32 v90, 2, v177
	v_mov_b32_e32 v91, v135
	v_cndmask_b32_e64 v81, v125, v77, s[8:9]
	v_lshl_add_u64 v[78:79], v[78:79], 0, v[90:91]
	s_and_b64 s[12:13], s[8:9], exec
	v_or_b32_e32 v80, v80, v136
	global_store_dwordx4 v[78:79], v[70:73], off offset:512 nt
	s_cselect_b32 s13, s28, s57
	s_cselect_b32 s12, s3, s56
	v_lshlrev_b64 v[78:79], 7, v[80:81]
	v_cndmask_b32_e64 v80, v148, v150, s[8:9]
	v_lshl_add_u64 v[78:79], s[12:13], 0, v[78:79]
	v_lshl_add_u32 v80, v80, 1, v245
	v_mov_b32_e32 v81, v135
	v_lshl_add_u64 v[78:79], v[78:79], 0, v[80:81]
	v_cvt_pk_bf16_f32 v80, v70, v71
	v_cvt_pk_bf16_f32 v81, v72, v73
	s_nop 1
	v_mov_b32_dpp v246, v80 quad_perm:[1,0,3,2] row_mask:0xf bank_mask:0xf
	v_mov_b32_dpp v247, v81 quad_perm:[1,0,3,2] row_mask:0xf bank_mask:0xf
	v_perm_b32 v246, v246, v80, v248
	v_perm_b32 v247, v247, v81, v248
	s_nop 1
	v_mov_b32_dpp v250, v246 quad_perm:[2,3,0,1] row_mask:0xf bank_mask:0xf
	v_mov_b32_dpp v251, v247 quad_perm:[2,3,0,1] row_mask:0xf bank_mask:0xf
	v_cndmask_b32_e64 v252, v246, v251, s[98:99]
	v_cndmask_b32_e64 v253, v250, v247, s[98:99]
	global_store_dwordx2 v[78:79], v[252:253], off

.LBB0_551:
	s_and_b64 vcc, exec, s[12:13]
	s_cbranch_vccz .LBB0_553
	s_and_b64 s[12:13], s[8:9], exec
	s_cselect_b32 s12, s89, 0xc100000
	v_mov_b32_e32 v80, s93
	s_add_u32 s12, s84, s12
	v_cndmask_b32_e64 v73, v69, v67, s[8:9]
	v_cndmask_b32_e64 v72, v68, v66, s[8:9]
	v_cndmask_b32_e64 v81, v80, v77, s[8:9]
	v_mov_b32_e32 v80, s67
	s_addc_u32 s13, s85, 0
	v_cndmask_b32_e64 v80, v80, v76, s[8:9]
	v_lshl_add_u64 v[72:73], s[12:13], 0, v[72:73]
	v_lshlrev_b32_e32 v82, 2, v177
	v_mov_b32_e32 v83, v135
	v_lshl_add_u64 v[72:73], v[72:73], 0, v[82:83]
	s_and_b64 s[12:13], s[8:9], exec
	v_or_b32_e32 v80, v80, v136
	global_store_dwordx4 v[72:73], v[62:65], off nt
	s_cselect_b32 s13, s28, s57
	s_cselect_b32 s12, s3, s56
	v_lshlrev_b64 v[72:73], 7, v[80:81]
	v_lshl_add_u64 v[72:73], s[12:13], 0, v[72:73]
	v_lshl_add_u32 v80, v138, 1, v245
	v_mov_b32_e32 v81, v135
	v_lshl_add_u64 v[72:73], v[72:73], 0, v[80:81]
	v_cvt_pk_bf16_f32 v80, v62, v63
	v_cvt_pk_bf16_f32 v81, v64, v65
	s_nop 1
	v_mov_b32_dpp v246, v80 quad_perm:[1,0,3,2] row_mask:0xf bank_mask:0xf
	v_mov_b32_dpp v247, v81 quad_perm:[1,0,3,2] row_mask:0xf bank_mask:0xf
	v_perm_b32 v246, v246, v80, v248
	v_perm_b32 v247, v247, v81, v248
	s_nop 1
	v_mov_b32_dpp v250, v246 quad_perm:[2,3,0,1] row_mask:0xf bank_mask:0xf
	v_mov_b32_dpp v251, v247 quad_perm:[2,3,0,1] row_mask:0xf bank_mask:0xf
	v_cndmask_b32_e64 v252, v246, v251, s[98:99]
	v_cndmask_b32_e64 v253, v250, v247, s[98:99]
	global_store_dwordx2 v[72:73], v[252:253], off

.LBB0_566:
	s_and_b64 vcc, exec, s[12:13]
	s_cbranch_vccz .LBB0_568
	s_and_b64 s[12:13], s[8:9], exec
	s_cselect_b32 s12, s89, 0xc100000
	s_add_u32 s12, s84, s12
	v_cndmask_b32_e64 v75, v69, v67, s[8:9]
	v_cndmask_b32_e64 v74, v68, v66, s[8:9]
	s_addc_u32 s13, s85, 0
	v_cndmask_b32_e64 v76, v60, v64, s[8:9]
	v_lshl_add_u64 v[74:75], s[12:13], 0, v[74:75]
	v_lshlrev_b32_e32 v80, 2, v177
	v_mov_b32_e32 v81, v135
	v_cndmask_b32_e64 v77, v61, v65, s[8:9]
	v_lshl_add_u64 v[74:75], v[74:75], 0, v[80:81]
	s_and_b64 s[12:13], s[8:9], exec
	v_or_b32_e32 v76, v76, v136
	global_store_dwordx4 v[74:75], v[54:57], off offset:512 nt
	s_cselect_b32 s13, s28, s57
	s_cselect_b32 s12, s3, s56
	v_lshlrev_b64 v[74:75], 7, v[76:77]
	v_lshl_add_u64 v[74:75], s[12:13], 0, v[74:75]
	v_lshl_add_u32 v76, v138, 1, v245
	v_mov_b32_e32 v77, v135
	v_lshl_add_u64 v[74:75], v[74:75], 0, v[76:77]
	v_cvt_pk_bf16_f32 v76, v54, v55
	v_cvt_pk_bf16_f32 v77, v56, v57
	s_nop 1
	v_mov_b32_dpp v246, v76 quad_perm:[1,0,3,2] row_mask:0xf bank_mask:0xf
	v_mov_b32_dpp v247, v77 quad_perm:[1,0,3,2] row_mask:0xf bank_mask:0xf
	v_perm_b32 v246, v246, v76, v248
	v_perm_b32 v247, v247, v77, v248
	s_nop 1
	v_mov_b32_dpp v250, v246 quad_perm:[2,3,0,1] row_mask:0xf bank_mask:0xf
	v_mov_b32_dpp v251, v247 quad_perm:[2,3,0,1] row_mask:0xf bank_mask:0xf
	v_cndmask_b32_e64 v252, v246, v251, s[98:99]
	v_cndmask_b32_e64 v253, v250, v247, s[98:99]
	global_store_dwordx2 v[74:75], v[252:253], off

.LBB0_581:
	s_and_b64 vcc, exec, s[12:13]
	s_cbranch_vccz .LBB0_583
	s_and_b64 s[12:13], s[8:9], exec
	s_cselect_b32 s12, s89, 0xc100000
	v_mov_b32_e32 v68, s93
	s_add_u32 s12, s84, s12
	v_cndmask_b32_e64 v57, v53, v51, s[8:9]
	v_cndmask_b32_e64 v56, v52, v50, s[8:9]
	v_cndmask_b32_e64 v69, v68, v65, s[8:9]
	v_mov_b32_e32 v68, s67
	s_addc_u32 s13, s85, 0
	v_cndmask_b32_e64 v68, v68, v64, s[8:9]
	v_lshl_add_u64 v[56:57], s[12:13], 0, v[56:57]
	v_lshlrev_b32_e32 v70, 2, v177
	v_mov_b32_e32 v71, v135
	v_lshl_add_u64 v[56:57], v[56:57], 0, v[70:71]
	s_and_b64 s[12:13], s[8:9], exec
	v_or_b32_e32 v68, v68, v136
	global_store_dwordx4 v[56:57], v[46:49], off nt
	s_cselect_b32 s13, s28, s57
	s_cselect_b32 s12, s3, s56
	v_lshlrev_b64 v[56:57], 7, v[68:69]
	v_lshl_add_u64 v[56:57], s[12:13], 0, v[56:57]
	v_lshl_add_u32 v68, v142, 1, v245
	v_mov_b32_e32 v69, v135
	v_lshl_add_u64 v[56:57], v[56:57], 0, v[68:69]
	v_cvt_pk_bf16_f32 v68, v46, v47
	v_cvt_pk_bf16_f32 v69, v48, v49
	s_nop 1
	v_mov_b32_dpp v246, v68 quad_perm:[1,0,3,2] row_mask:0xf bank_mask:0xf
	v_mov_b32_dpp v247, v69 quad_perm:[1,0,3,2] row_mask:0xf bank_mask:0xf
	v_perm_b32 v246, v246, v68, v248
	v_perm_b32 v247, v247, v69, v248
	s_nop 1
	v_mov_b32_dpp v250, v246 quad_perm:[2,3,0,1] row_mask:0xf bank_mask:0xf
	v_mov_b32_dpp v251, v247 quad_perm:[2,3,0,1] row_mask:0xf bank_mask:0xf
	v_cndmask_b32_e64 v252, v246, v251, s[98:99]
	v_cndmask_b32_e64 v253, v250, v247, s[98:99]
	global_store_dwordx2 v[56:57], v[252:253], off

.LBB0_596:
	s_and_b64 vcc, exec, s[12:13]
	s_cbranch_vccz .LBB0_598
	s_and_b64 s[12:13], s[8:9], exec
	s_cselect_b32 s12, s89, 0xc100000
	s_add_u32 s12, s84, s12
	v_cndmask_b32_e64 v47, v53, v51, s[8:9]
	v_cndmask_b32_e64 v46, v52, v50, s[8:9]
	s_addc_u32 s13, s85, 0
	v_cndmask_b32_e64 v48, v60, v44, s[8:9]
	v_lshl_add_u64 v[46:47], s[12:13], 0, v[46:47]
	v_lshlrev_b32_e32 v62, 2, v177
	v_mov_b32_e32 v63, v135
	v_cndmask_b32_e64 v49, v61, v45, s[8:9]
	v_lshl_add_u64 v[46:47], v[46:47], 0, v[62:63]
	s_and_b64 s[12:13], s[8:9], exec
	v_or_b32_e32 v48, v48, v136
	global_store_dwordx4 v[46:47], v[38:41], off offset:512 nt
	s_cselect_b32 s13, s28, s57
	s_cselect_b32 s12, s3, s56
	v_lshlrev_b64 v[46:47], 7, v[48:49]
	v_lshl_add_u64 v[46:47], s[12:13], 0, v[46:47]
	v_lshl_add_u32 v48, v142, 1, v245
	v_mov_b32_e32 v49, v135
	v_lshl_add_u64 v[46:47], v[46:47], 0, v[48:49]
	v_cvt_pk_bf16_f32 v48, v38, v39
	v_cvt_pk_bf16_f32 v49, v40, v41
	s_nop 1
	v_mov_b32_dpp v246, v48 quad_perm:[1,0,3,2] row_mask:0xf bank_mask:0xf
	v_mov_b32_dpp v247, v49 quad_perm:[1,0,3,2] row_mask:0xf bank_mask:0xf
	v_perm_b32 v246, v246, v48, v248
	v_perm_b32 v247, v247, v49, v248
	s_nop 1
	v_mov_b32_dpp v250, v246 quad_perm:[2,3,0,1] row_mask:0xf bank_mask:0xf
	v_mov_b32_dpp v251, v247 quad_perm:[2,3,0,1] row_mask:0xf bank_mask:0xf
	v_cndmask_b32_e64 v252, v246, v251, s[98:99]
	v_cndmask_b32_e64 v253, v250, v247, s[98:99]
	global_store_dwordx2 v[46:47], v[252:253], off

.LBB0_611:
	s_and_b64 vcc, exec, s[12:13]
	s_cbranch_vccz .LBB0_613
	s_and_b64 s[12:13], s[8:9], exec
	s_cselect_b32 s12, s89, 0xc100000
	v_mov_b32_e32 v48, s93
	s_add_u32 s12, s84, s12
	v_cndmask_b32_e64 v41, v37, v35, s[8:9]
	v_cndmask_b32_e64 v40, v36, v34, s[8:9]
	v_cndmask_b32_e64 v49, v48, v45, s[8:9]
	v_mov_b32_e32 v48, s67
	s_addc_u32 s13, s85, 0
	v_cndmask_b32_e64 v48, v48, v44, s[8:9]
	v_lshl_add_u64 v[40:41], s[12:13], 0, v[40:41]
	v_lshlrev_b32_e32 v50, 2, v177
	v_mov_b32_e32 v51, v135
	v_lshl_add_u64 v[40:41], v[40:41], 0, v[50:51]
	s_and_b64 s[12:13], s[8:9], exec
	v_or_b32_e32 v48, v48, v136
	global_store_dwordx4 v[40:41], v[30:33], off nt
	s_cselect_b32 s13, s28, s57
	s_cselect_b32 s12, s3, s56
	v_lshlrev_b64 v[40:41], 7, v[48:49]
	v_cndmask_b32_e64 v48, v146, v138, s[8:9]
	v_lshl_add_u64 v[40:41], s[12:13], 0, v[40:41]
	v_lshl_add_u32 v48, v48, 1, v245
	v_mov_b32_e32 v49, v135
	v_lshl_add_u64 v[40:41], v[40:41], 0, v[48:49]
	v_cvt_pk_bf16_f32 v48, v30, v31
	v_cvt_pk_bf16_f32 v49, v32, v33
	s_nop 1
	v_mov_b32_dpp v246, v48 quad_perm:[1,0,3,2] row_mask:0xf bank_mask:0xf
	v_mov_b32_dpp v247, v49 quad_perm:[1,0,3,2] row_mask:0xf bank_mask:0xf
	v_perm_b32 v246, v246, v48, v248
	v_perm_b32 v247, v247, v49, v248
	s_nop 1
	v_mov_b32_dpp v250, v246 quad_perm:[2,3,0,1] row_mask:0xf bank_mask:0xf
	v_mov_b32_dpp v251, v247 quad_perm:[2,3,0,1] row_mask:0xf bank_mask:0xf
	v_cndmask_b32_e64 v252, v246, v251, s[98:99]
	v_cndmask_b32_e64 v253, v250, v247, s[98:99]
	global_store_dwordx2 v[40:41], v[252:253], off

.LBB0_626:
	s_and_b64 vcc, exec, s[12:13]
	s_cbranch_vccz .LBB0_628
	s_and_b64 s[12:13], s[8:9], exec
	s_cselect_b32 s12, s89, 0xc100000
	s_add_u32 s12, s84, s12
	v_cndmask_b32_e64 v31, v37, v35, s[8:9]
	v_cndmask_b32_e64 v30, v36, v34, s[8:9]
	s_addc_u32 s13, s85, 0
	v_cndmask_b32_e64 v32, v60, v28, s[8:9]
	v_lshl_add_u64 v[30:31], s[12:13], 0, v[30:31]
	v_lshlrev_b32_e32 v42, 2, v177
	v_mov_b32_e32 v43, v135
	v_cndmask_b32_e64 v33, v61, v29, s[8:9]
	v_lshl_add_u64 v[30:31], v[30:31], 0, v[42:43]
	s_and_b64 s[12:13], s[8:9], exec
	v_or_b32_e32 v32, v32, v136
	global_store_dwordx4 v[30:31], v[22:25], off offset:512 nt
	s_cselect_b32 s13, s28, s57
	s_cselect_b32 s12, s3, s56
	v_lshlrev_b64 v[30:31], 7, v[32:33]
	v_cndmask_b32_e64 v32, v146, v138, s[8:9]
	v_lshl_add_u64 v[30:31], s[12:13], 0, v[30:31]
	v_lshl_add_u32 v32, v32, 1, v245
	v_mov_b32_e32 v33, v135
	v_lshl_add_u64 v[30:31], v[30:31], 0, v[32:33]
	v_cvt_pk_bf16_f32 v32, v22, v23
	v_cvt_pk_bf16_f32 v33, v24, v25
	s_nop 1
	v_mov_b32_dpp v246, v32 quad_perm:[1,0,3,2] row_mask:0xf bank_mask:0xf
	v_mov_b32_dpp v247, v33 quad_perm:[1,0,3,2] row_mask:0xf bank_mask:0xf
	v_perm_b32 v246, v246, v32, v248
	v_perm_b32 v247, v247, v33, v248
	s_nop 1
	v_mov_b32_dpp v250, v246 quad_perm:[2,3,0,1] row_mask:0xf bank_mask:0xf
	v_mov_b32_dpp v251, v247 quad_perm:[2,3,0,1] row_mask:0xf bank_mask:0xf
	v_cndmask_b32_e64 v252, v246, v251, s[98:99]
	v_cndmask_b32_e64 v253, v250, v247, s[98:99]
	global_store_dwordx2 v[30:31], v[252:253], off

.LBB0_641:
	s_and_b64 vcc, exec, s[12:13]
	s_cbranch_vccz .LBB0_643
	s_and_b64 s[12:13], s[8:9], exec
	s_cselect_b32 s12, s89, 0xc100000
	v_mov_b32_e32 v32, s93
	s_add_u32 s12, s84, s12
	v_cndmask_b32_e64 v25, v21, v19, s[8:9]
	v_cndmask_b32_e64 v24, v20, v18, s[8:9]
	v_cndmask_b32_e64 v33, v32, v29, s[8:9]
	v_mov_b32_e32 v32, s67
	s_addc_u32 s13, s85, 0
	v_cndmask_b32_e64 v32, v32, v28, s[8:9]
	v_lshl_add_u64 v[24:25], s[12:13], 0, v[24:25]
	v_lshlrev_b32_e32 v34, 2, v177
	v_mov_b32_e32 v35, v135
	v_lshl_add_u64 v[24:25], v[24:25], 0, v[34:35]
	s_and_b64 s[12:13], s[8:9], exec
	v_or_b32_e32 v32, v32, v136
	global_store_dwordx4 v[24:25], v[14:17], off nt
	s_cselect_b32 s13, s28, s57
	s_cselect_b32 s12, s3, s56
	v_lshlrev_b64 v[24:25], 7, v[32:33]
	v_cndmask_b32_e64 v32, v148, v150, s[8:9]
	v_lshl_add_u64 v[24:25], s[12:13], 0, v[24:25]
	v_lshl_add_u32 v32, v32, 1, v245
	v_mov_b32_e32 v33, v135
	v_lshl_add_u64 v[24:25], v[24:25], 0, v[32:33]
	v_cvt_pk_bf16_f32 v32, v14, v15
	v_cvt_pk_bf16_f32 v33, v16, v17
	s_nop 1
	v_mov_b32_dpp v246, v32 quad_perm:[1,0,3,2] row_mask:0xf bank_mask:0xf
	v_mov_b32_dpp v247, v33 quad_perm:[1,0,3,2] row_mask:0xf bank_mask:0xf
	v_perm_b32 v246, v246, v32, v248
	v_perm_b32 v247, v247, v33, v248
	s_nop 1
	v_mov_b32_dpp v250, v246 quad_perm:[2,3,0,1] row_mask:0xf bank_mask:0xf
	v_mov_b32_dpp v251, v247 quad_perm:[2,3,0,1] row_mask:0xf bank_mask:0xf
	v_cndmask_b32_e64 v252, v246, v251, s[98:99]
	v_cndmask_b32_e64 v253, v250, v247, s[98:99]
	global_store_dwordx2 v[24:25], v[252:253], off

.LBB0_656:
	s_and_b64 vcc, exec, s[12:13]
	s_cbranch_vccz .LBB0_658
	s_and_b64 s[12:13], s[8:9], exec
	s_cselect_b32 s12, s89, 0xc100000
	s_add_u32 s12, s84, s12
	v_cndmask_b32_e64 v15, v21, v19, s[8:9]
	v_cndmask_b32_e64 v14, v20, v18, s[8:9]
	s_addc_u32 s13, s85, 0
	v_cndmask_b32_e64 v16, v60, v12, s[8:9]
	v_lshl_add_u64 v[14:15], s[12:13], 0, v[14:15]
	v_lshlrev_b32_e32 v26, 2, v177
	v_mov_b32_e32 v27, v135
	v_cndmask_b32_e64 v17, v61, v13, s[8:9]
	v_lshl_add_u64 v[14:15], v[14:15], 0, v[26:27]
	s_and_b64 s[12:13], s[8:9], exec
	v_or_b32_e32 v16, v16, v136
	global_store_dwordx4 v[14:15], v[6:9], off offset:512 nt
	s_cselect_b32 s13, s28, s57
	s_cselect_b32 s12, s3, s56
	v_lshlrev_b64 v[14:15], 7, v[16:17]
	v_cndmask_b32_e64 v16, v148, v150, s[8:9]
	v_lshl_add_u64 v[14:15], s[12:13], 0, v[14:15]
	v_lshl_add_u32 v16, v16, 1, v245
	v_mov_b32_e32 v17, v135
	v_lshl_add_u64 v[14:15], v[14:15], 0, v[16:17]
	v_cvt_pk_bf16_f32 v16, v6, v7
	v_cvt_pk_bf16_f32 v17, v8, v9
	s_nop 1
	v_mov_b32_dpp v246, v16 quad_perm:[1,0,3,2] row_mask:0xf bank_mask:0xf
	v_mov_b32_dpp v247, v17 quad_perm:[1,0,3,2] row_mask:0xf bank_mask:0xf
	v_perm_b32 v246, v246, v16, v248
	v_perm_b32 v247, v247, v17, v248
	s_nop 1
	v_mov_b32_dpp v250, v246 quad_perm:[2,3,0,1] row_mask:0xf bank_mask:0xf
	v_mov_b32_dpp v251, v247 quad_perm:[2,3,0,1] row_mask:0xf bank_mask:0xf
	v_cndmask_b32_e64 v252, v246, v251, s[98:99]
	v_cndmask_b32_e64 v253, v250, v247, s[98:99]
	global_store_dwordx2 v[14:15], v[252:253], off

.LBB0_679:
	s_and_b64 vcc, exec, s[12:13]
	s_cbranch_vccz .LBB0_681
	s_and_b64 s[12:13], s[8:9], exec
	s_cselect_b32 s12, s89, 0xc100000
	s_add_u32 s12, s84, s12
	v_cndmask_b32_e64 v119, v167, v165, s[8:9]
	v_cndmask_b32_e64 v118, v166, v164, s[8:9]
	s_addc_u32 s13, s85, 0
	v_cndmask_b32_e64 v121, v125, v129, s[8:9]
	v_cndmask_b32_e64 v120, v175, v128, s[8:9]
	v_lshl_add_u64 v[118:119], s[12:13], 0, v[118:119]
	v_lshlrev_b32_e32 v128, 2, v177
	v_mov_b32_e32 v129, v135
	v_lshl_add_u64 v[118:119], v[118:119], 0, v[128:129]
	s_and_b64 s[12:13], s[8:9], exec
	v_and_or_b32 v120, v124, s94, v120
	global_store_dwordx4 v[118:119], v[114:117], off offset:576 nt
	s_cselect_b32 s13, s28, s57
	s_cselect_b32 s12, s3, s56
	v_lshlrev_b64 v[118:119], 7, v[120:121]
	v_lshl_add_u64 v[118:119], s[12:13], 0, v[118:119]
	v_lshl_add_u32 v120, v138, 1, v245
	v_mov_b32_e32 v121, v135
	v_lshl_add_u64 v[118:119], v[118:119], 0, v[120:121]
	v_cvt_pk_bf16_f32 v120, v114, v115
	v_cvt_pk_bf16_f32 v121, v116, v117
	s_nop 1
	v_mov_b32_dpp v246, v120 quad_perm:[1,0,3,2] row_mask:0xf bank_mask:0xf
	v_mov_b32_dpp v247, v121 quad_perm:[1,0,3,2] row_mask:0xf bank_mask:0xf
	v_perm_b32 v246, v246, v120, v248
	v_perm_b32 v247, v247, v121, v248
	s_nop 1
	v_mov_b32_dpp v250, v246 quad_perm:[2,3,0,1] row_mask:0xf bank_mask:0xf
	v_mov_b32_dpp v251, v247 quad_perm:[2,3,0,1] row_mask:0xf bank_mask:0xf
	v_cndmask_b32_e64 v252, v246, v251, s[98:99]
	v_cndmask_b32_e64 v253, v250, v247, s[98:99]
	global_store_dwordx2 v[118:119], v[252:253], off

.LBB0_698:
	s_and_b64 vcc, exec, s[12:13]
	s_cbranch_vccz .LBB0_700
	s_and_b64 s[12:13], s[8:9], exec
	s_cselect_b32 s12, s89, 0xc100000
	v_mov_b32_e32 v112, s93
	s_add_u32 s12, s84, s12
	v_cndmask_b32_e64 v111, v117, v115, s[8:9]
	v_cndmask_b32_e64 v110, v116, v114, s[8:9]
	v_cndmask_b32_e64 v113, v112, v129, s[8:9]
	v_mov_b32_e32 v112, s71
	s_addc_u32 s13, s85, 0
	v_cndmask_b32_e64 v112, v112, v128, s[8:9]
	v_lshl_add_u64 v[110:111], s[12:13], 0, v[110:111]
	v_lshlrev_b32_e32 v128, 2, v177
	v_mov_b32_e32 v129, v135
	v_lshl_add_u64 v[110:111], v[110:111], 0, v[128:129]
	s_and_b64 s[12:13], s[8:9], exec
	v_and_or_b32 v112, v178, s94, v112
	global_store_dwordx4 v[110:111], v[106:109], off offset:64 nt
	s_cselect_b32 s13, s28, s57
	s_cselect_b32 s12, s3, s56
	v_lshlrev_b64 v[110:111], 7, v[112:113]
	v_lshl_add_u64 v[110:111], s[12:13], 0, v[110:111]
	v_lshl_add_u32 v112, v142, 1, v245
	v_mov_b32_e32 v113, v135
	v_lshl_add_u64 v[110:111], v[110:111], 0, v[112:113]
	v_cvt_pk_bf16_f32 v112, v106, v107
	v_cvt_pk_bf16_f32 v113, v108, v109
	s_nop 1
	v_mov_b32_dpp v246, v112 quad_perm:[1,0,3,2] row_mask:0xf bank_mask:0xf
	v_mov_b32_dpp v247, v113 quad_perm:[1,0,3,2] row_mask:0xf bank_mask:0xf
	v_perm_b32 v246, v246, v112, v248
	v_perm_b32 v247, v247, v113, v248
	s_nop 1
	v_mov_b32_dpp v250, v246 quad_perm:[2,3,0,1] row_mask:0xf bank_mask:0xf
	v_mov_b32_dpp v251, v247 quad_perm:[2,3,0,1] row_mask:0xf bank_mask:0xf
	v_cndmask_b32_e64 v252, v246, v251, s[98:99]
	v_cndmask_b32_e64 v253, v250, v247, s[98:99]
	global_store_dwordx2 v[110:111], v[252:253], off

.LBB0_717:
	s_and_b64 vcc, exec, s[12:13]
	s_cbranch_vccz .LBB0_719
	s_and_b64 s[12:13], s[8:9], exec
	s_cselect_b32 s12, s89, 0xc100000
	s_add_u32 s12, s84, s12
	v_cndmask_b32_e64 v103, v117, v115, s[8:9]
	v_cndmask_b32_e64 v102, v116, v114, s[8:9]
	s_addc_u32 s13, s85, 0
	v_cndmask_b32_e64 v105, v125, v109, s[8:9]
	v_cndmask_b32_e64 v104, v175, v108, s[8:9]
	v_lshl_add_u64 v[102:103], s[12:13], 0, v[102:103]
	v_lshlrev_b32_e32 v108, 2, v177
	v_mov_b32_e32 v109, v135
	v_lshl_add_u64 v[102:103], v[102:103], 0, v[108:109]
	s_and_b64 s[12:13], s[8:9], exec
	v_and_or_b32 v104, v124, s94, v104
	global_store_dwordx4 v[102:103], v[98:101], off offset:576 nt
	s_cselect_b32 s13, s28, s57
	s_cselect_b32 s12, s3, s56
	v_lshlrev_b64 v[102:103], 7, v[104:105]
	v_lshl_add_u64 v[102:103], s[12:13], 0, v[102:103]
	v_lshl_add_u32 v104, v142, 1, v245
	v_mov_b32_e32 v105, v135
	v_lshl_add_u64 v[102:103], v[102:103], 0, v[104:105]
	v_cvt_pk_bf16_f32 v104, v98, v99
	v_cvt_pk_bf16_f32 v105, v100, v101
	s_nop 1
	v_mov_b32_dpp v246, v104 quad_perm:[1,0,3,2] row_mask:0xf bank_mask:0xf
	v_mov_b32_dpp v247, v105 quad_perm:[1,0,3,2] row_mask:0xf bank_mask:0xf
	v_perm_b32 v246, v246, v104, v248
	v_perm_b32 v247, v247, v105, v248
	s_nop 1
	v_mov_b32_dpp v250, v246 quad_perm:[2,3,0,1] row_mask:0xf bank_mask:0xf
	v_mov_b32_dpp v251, v247 quad_perm:[2,3,0,1] row_mask:0xf bank_mask:0xf
	v_cndmask_b32_e64 v252, v246, v251, s[98:99]
	v_cndmask_b32_e64 v253, v250, v247, s[98:99]
	global_store_dwordx2 v[102:103], v[252:253], off

.LBB0_736:
	s_and_b64 vcc, exec, s[12:13]
	s_cbranch_vccz .LBB0_738
	s_and_b64 s[12:13], s[8:9], exec
	s_cselect_b32 s12, s89, 0xc100000
	v_mov_b32_e32 v96, s93
	s_add_u32 s12, s84, s12
	v_cndmask_b32_e64 v95, v101, v99, s[8:9]
	v_cndmask_b32_e64 v94, v100, v98, s[8:9]
	v_cndmask_b32_e64 v97, v96, v109, s[8:9]
	v_mov_b32_e32 v96, s71
	s_addc_u32 s13, s85, 0
	v_cndmask_b32_e64 v96, v96, v108, s[8:9]
	v_lshl_add_u64 v[94:95], s[12:13], 0, v[94:95]
	v_lshlrev_b32_e32 v108, 2, v177
	v_mov_b32_e32 v109, v135
	v_lshl_add_u64 v[94:95], v[94:95], 0, v[108:109]
	s_and_b64 s[12:13], s[8:9], exec
	v_and_or_b32 v96, v178, s94, v96
	global_store_dwordx4 v[94:95], v[90:93], off offset:64 nt
	s_cselect_b32 s13, s28, s57
	s_cselect_b32 s12, s3, s56
	v_lshlrev_b64 v[94:95], 7, v[96:97]
	v_cndmask_b32_e64 v96, v146, v138, s[8:9]
	v_lshl_add_u64 v[94:95], s[12:13], 0, v[94:95]
	v_lshl_add_u32 v96, v96, 1, v245
	v_mov_b32_e32 v97, v135
	v_lshl_add_u64 v[94:95], v[94:95], 0, v[96:97]
	v_cvt_pk_bf16_f32 v96, v90, v91
	v_cvt_pk_bf16_f32 v97, v92, v93
	s_nop 1
	v_mov_b32_dpp v246, v96 quad_perm:[1,0,3,2] row_mask:0xf bank_mask:0xf
	v_mov_b32_dpp v247, v97 quad_perm:[1,0,3,2] row_mask:0xf bank_mask:0xf
	v_perm_b32 v246, v246, v96, v248
	v_perm_b32 v247, v247, v97, v248
	s_nop 1
	v_mov_b32_dpp v250, v246 quad_perm:[2,3,0,1] row_mask:0xf bank_mask:0xf
	v_mov_b32_dpp v251, v247 quad_perm:[2,3,0,1] row_mask:0xf bank_mask:0xf
	v_cndmask_b32_e64 v252, v246, v251, s[98:99]
	v_cndmask_b32_e64 v253, v250, v247, s[98:99]
	global_store_dwordx2 v[94:95], v[252:253], off

.LBB0_755:
	s_and_b64 vcc, exec, s[12:13]
	s_cbranch_vccz .LBB0_757
	s_and_b64 s[12:13], s[8:9], exec
	s_cselect_b32 s12, s89, 0xc100000
	s_add_u32 s12, s84, s12
	v_cndmask_b32_e64 v87, v101, v99, s[8:9]
	v_cndmask_b32_e64 v86, v100, v98, s[8:9]
	s_addc_u32 s13, s85, 0
	v_cndmask_b32_e64 v89, v125, v93, s[8:9]
	v_cndmask_b32_e64 v88, v175, v92, s[8:9]
	v_lshl_add_u64 v[86:87], s[12:13], 0, v[86:87]
	v_lshlrev_b32_e32 v92, 2, v177
	v_mov_b32_e32 v93, v135
	v_lshl_add_u64 v[86:87], v[86:87], 0, v[92:93]
	s_and_b64 s[12:13], s[8:9], exec
	v_and_or_b32 v88, v124, s94, v88
	global_store_dwordx4 v[86:87], v[82:85], off offset:576 nt
	s_cselect_b32 s13, s28, s57
	s_cselect_b32 s12, s3, s56
	v_lshlrev_b64 v[86:87], 7, v[88:89]
	v_cndmask_b32_e64 v88, v146, v138, s[8:9]
	v_lshl_add_u64 v[86:87], s[12:13], 0, v[86:87]
	v_lshl_add_u32 v88, v88, 1, v245
	v_mov_b32_e32 v89, v135
	v_lshl_add_u64 v[86:87], v[86:87], 0, v[88:89]
	v_cvt_pk_bf16_f32 v88, v82, v83
	v_cvt_pk_bf16_f32 v89, v84, v85
	s_nop 1
	v_mov_b32_dpp v246, v88 quad_perm:[1,0,3,2] row_mask:0xf bank_mask:0xf
	v_mov_b32_dpp v247, v89 quad_perm:[1,0,3,2] row_mask:0xf bank_mask:0xf
	v_perm_b32 v246, v246, v88, v248
	v_perm_b32 v247, v247, v89, v248
	s_nop 1
	v_mov_b32_dpp v250, v246 quad_perm:[2,3,0,1] row_mask:0xf bank_mask:0xf
	v_mov_b32_dpp v251, v247 quad_perm:[2,3,0,1] row_mask:0xf bank_mask:0xf
	v_cndmask_b32_e64 v252, v246, v251, s[98:99]
	v_cndmask_b32_e64 v253, v250, v247, s[98:99]
	global_store_dwordx2 v[86:87], v[252:253], off

.LBB0_774:
	s_and_b64 vcc, exec, s[12:13]
	s_cbranch_vccz .LBB0_776
	s_and_b64 s[12:13], s[8:9], exec
	s_cselect_b32 s12, s89, 0xc100000
	v_mov_b32_e32 v80, s93
	s_add_u32 s12, s84, s12
	v_cndmask_b32_e64 v79, v85, v83, s[8:9]
	v_cndmask_b32_e64 v78, v84, v82, s[8:9]
	v_cndmask_b32_e64 v81, v80, v93, s[8:9]
	v_mov_b32_e32 v80, s71
	s_addc_u32 s13, s85, 0
	v_cndmask_b32_e64 v80, v80, v92, s[8:9]
	v_lshl_add_u64 v[78:79], s[12:13], 0, v[78:79]
	v_lshlrev_b32_e32 v92, 2, v177
	v_mov_b32_e32 v93, v135
	v_lshl_add_u64 v[78:79], v[78:79], 0, v[92:93]
	s_and_b64 s[12:13], s[8:9], exec
	v_and_or_b32 v80, v178, s94, v80
	global_store_dwordx4 v[78:79], v[74:77], off offset:64 nt
	s_cselect_b32 s13, s28, s57
	s_cselect_b32 s12, s3, s56
	v_lshlrev_b64 v[78:79], 7, v[80:81]
	v_cndmask_b32_e64 v80, v148, v150, s[8:9]
	v_lshl_add_u64 v[78:79], s[12:13], 0, v[78:79]
	v_lshl_add_u32 v80, v80, 1, v245
	v_mov_b32_e32 v81, v135
	v_lshl_add_u64 v[78:79], v[78:79], 0, v[80:81]
	v_cvt_pk_bf16_f32 v80, v74, v75
	v_cvt_pk_bf16_f32 v81, v76, v77
	s_nop 1
	v_mov_b32_dpp v246, v80 quad_perm:[1,0,3,2] row_mask:0xf bank_mask:0xf
	v_mov_b32_dpp v247, v81 quad_perm:[1,0,3,2] row_mask:0xf bank_mask:0xf
	v_perm_b32 v246, v246, v80, v248
	v_perm_b32 v247, v247, v81, v248
	s_nop 1
	v_mov_b32_dpp v250, v246 quad_perm:[2,3,0,1] row_mask:0xf bank_mask:0xf
	v_mov_b32_dpp v251, v247 quad_perm:[2,3,0,1] row_mask:0xf bank_mask:0xf
	v_cndmask_b32_e64 v252, v246, v251, s[98:99]
	v_cndmask_b32_e64 v253, v250, v247, s[98:99]
	global_store_dwordx2 v[78:79], v[252:253], off

.LBB0_793:
	s_and_b64 vcc, exec, s[12:13]
	s_cbranch_vccz .LBB0_795
	s_and_b64 s[12:13], s[8:9], exec
	s_cselect_b32 s12, s89, 0xc100000
	s_add_u32 s12, s84, s12
	v_cndmask_b32_e64 v71, v85, v83, s[8:9]
	v_cndmask_b32_e64 v70, v84, v82, s[8:9]
	s_addc_u32 s13, s85, 0
	v_cndmask_b32_e64 v73, v125, v77, s[8:9]
	v_cndmask_b32_e64 v72, v175, v76, s[8:9]
	v_lshl_add_u64 v[70:71], s[12:13], 0, v[70:71]
	v_lshlrev_b32_e32 v76, 2, v177
	v_mov_b32_e32 v77, v135
	v_lshl_add_u64 v[70:71], v[70:71], 0, v[76:77]
	s_and_b64 s[12:13], s[8:9], exec
	v_and_or_b32 v72, v124, s94, v72
	global_store_dwordx4 v[70:71], v[66:69], off offset:576 nt
	s_cselect_b32 s13, s28, s57
	s_cselect_b32 s12, s3, s56
	v_lshlrev_b64 v[70:71], 7, v[72:73]
	v_cndmask_b32_e64 v72, v148, v150, s[8:9]
	v_lshl_add_u64 v[70:71], s[12:13], 0, v[70:71]
	v_lshl_add_u32 v72, v72, 1, v245
	v_mov_b32_e32 v73, v135
	v_lshl_add_u64 v[70:71], v[70:71], 0, v[72:73]
	v_cvt_pk_bf16_f32 v72, v66, v67
	v_cvt_pk_bf16_f32 v73, v68, v69
	s_nop 1
	v_mov_b32_dpp v246, v72 quad_perm:[1,0,3,2] row_mask:0xf bank_mask:0xf
	v_mov_b32_dpp v247, v73 quad_perm:[1,0,3,2] row_mask:0xf bank_mask:0xf
	v_perm_b32 v246, v246, v72, v248
	v_perm_b32 v247, v247, v73, v248
	s_nop 1
	v_mov_b32_dpp v250, v246 quad_perm:[2,3,0,1] row_mask:0xf bank_mask:0xf
	v_mov_b32_dpp v251, v247 quad_perm:[2,3,0,1] row_mask:0xf bank_mask:0xf
	v_cndmask_b32_e64 v252, v246, v251, s[98:99]
	v_cndmask_b32_e64 v253, v250, v247, s[98:99]
	global_store_dwordx2 v[70:71], v[252:253], off

.LBB0_812:
	s_and_b64 vcc, exec, s[12:13]
	s_cbranch_vccz .LBB0_814
	s_and_b64 s[12:13], s[8:9], exec
	s_cselect_b32 s12, s89, 0xc100000
	v_mov_b32_e32 v64, s93
	s_add_u32 s12, s84, s12
	v_cndmask_b32_e64 v63, v69, v67, s[8:9]
	v_cndmask_b32_e64 v62, v68, v66, s[8:9]
	v_cndmask_b32_e64 v65, v64, v77, s[8:9]
	v_mov_b32_e32 v64, s67
	s_addc_u32 s13, s85, 0
	v_cndmask_b32_e64 v64, v64, v76, s[8:9]
	v_lshl_add_u64 v[62:63], s[12:13], 0, v[62:63]
	v_lshlrev_b32_e32 v76, 2, v177
	v_mov_b32_e32 v77, v135
	v_lshl_add_u64 v[62:63], v[62:63], 0, v[76:77]
	s_and_b64 s[12:13], s[8:9], exec
	v_and_or_b32 v64, v178, s94, v64
	global_store_dwordx4 v[62:63], v[58:61], off offset:64 nt
	s_cselect_b32 s13, s28, s57
	s_cselect_b32 s12, s3, s56
	v_lshlrev_b64 v[62:63], 7, v[64:65]
	v_lshl_add_u64 v[62:63], s[12:13], 0, v[62:63]
	v_lshl_add_u32 v64, v138, 1, v245
	v_mov_b32_e32 v65, v135
	v_lshl_add_u64 v[62:63], v[62:63], 0, v[64:65]
	v_cvt_pk_bf16_f32 v64, v58, v59
	v_cvt_pk_bf16_f32 v65, v60, v61
	s_nop 1
	v_mov_b32_dpp v246, v64 quad_perm:[1,0,3,2] row_mask:0xf bank_mask:0xf
	v_mov_b32_dpp v247, v65 quad_perm:[1,0,3,2] row_mask:0xf bank_mask:0xf
	v_perm_b32 v246, v246, v64, v248
	v_perm_b32 v247, v247, v65, v248
	s_nop 1
	v_mov_b32_dpp v250, v246 quad_perm:[2,3,0,1] row_mask:0xf bank_mask:0xf
	v_mov_b32_dpp v251, v247 quad_perm:[2,3,0,1] row_mask:0xf bank_mask:0xf
	v_cndmask_b32_e64 v252, v246, v251, s[98:99]
	v_cndmask_b32_e64 v253, v250, v247, s[98:99]
	global_store_dwordx2 v[62:63], v[252:253], off

.LBB0_831:
	s_and_b64 vcc, exec, s[12:13]
	s_cbranch_vccz .LBB0_833
	s_and_b64 s[12:13], s[8:9], exec
	s_cselect_b32 s12, s89, 0xc100000
	s_add_u32 s12, s84, s12
	v_cndmask_b32_e64 v55, v69, v67, s[8:9]
	v_cndmask_b32_e64 v54, v68, v66, s[8:9]
	s_addc_u32 s13, s85, 0
	v_cndmask_b32_e64 v57, v61, v65, s[8:9]
	v_cndmask_b32_e64 v56, v60, v64, s[8:9]
	v_lshl_add_u64 v[54:55], s[12:13], 0, v[54:55]
	v_lshlrev_b32_e32 v64, 2, v177
	v_mov_b32_e32 v65, v135
	v_lshl_add_u64 v[54:55], v[54:55], 0, v[64:65]
	s_and_b64 s[12:13], s[8:9], exec
	v_and_or_b32 v56, v124, s94, v56
	global_store_dwordx4 v[54:55], v[50:53], off offset:576 nt
	s_cselect_b32 s13, s28, s57
	s_cselect_b32 s12, s3, s56
	v_lshlrev_b64 v[54:55], 7, v[56:57]
	v_lshl_add_u64 v[54:55], s[12:13], 0, v[54:55]
	v_lshl_add_u32 v56, v138, 1, v245
	v_mov_b32_e32 v57, v135
	v_lshl_add_u64 v[54:55], v[54:55], 0, v[56:57]
	v_cvt_pk_bf16_f32 v56, v50, v51
	v_cvt_pk_bf16_f32 v57, v52, v53
	s_nop 1
	v_mov_b32_dpp v246, v56 quad_perm:[1,0,3,2] row_mask:0xf bank_mask:0xf
	v_mov_b32_dpp v247, v57 quad_perm:[1,0,3,2] row_mask:0xf bank_mask:0xf
	v_perm_b32 v246, v246, v56, v248
	v_perm_b32 v247, v247, v57, v248
	s_nop 1
	v_mov_b32_dpp v250, v246 quad_perm:[2,3,0,1] row_mask:0xf bank_mask:0xf
	v_mov_b32_dpp v251, v247 quad_perm:[2,3,0,1] row_mask:0xf bank_mask:0xf
	v_cndmask_b32_e64 v252, v246, v251, s[98:99]
	v_cndmask_b32_e64 v253, v250, v247, s[98:99]
	global_store_dwordx2 v[54:55], v[252:253], off

.LBB0_850:
	s_and_b64 vcc, exec, s[12:13]
	s_cbranch_vccz .LBB0_852
	s_and_b64 s[12:13], s[8:9], exec
	s_cselect_b32 s12, s89, 0xc100000
	v_mov_b32_e32 v48, s93
	s_add_u32 s12, s84, s12
	v_cndmask_b32_e64 v47, v53, v51, s[8:9]
	v_cndmask_b32_e64 v46, v52, v50, s[8:9]
	v_cndmask_b32_e64 v49, v48, v65, s[8:9]
	v_mov_b32_e32 v48, s67
	s_addc_u32 s13, s85, 0
	v_cndmask_b32_e64 v48, v48, v64, s[8:9]
	v_lshl_add_u64 v[46:47], s[12:13], 0, v[46:47]
	v_lshlrev_b32_e32 v64, 2, v177
	v_mov_b32_e32 v65, v135
	v_lshl_add_u64 v[46:47], v[46:47], 0, v[64:65]
	s_and_b64 s[12:13], s[8:9], exec
	v_and_or_b32 v48, v178, s94, v48
	global_store_dwordx4 v[46:47], v[42:45], off offset:64 nt
	s_cselect_b32 s13, s28, s57
	s_cselect_b32 s12, s3, s56
	v_lshlrev_b64 v[46:47], 7, v[48:49]
	v_lshl_add_u64 v[46:47], s[12:13], 0, v[46:47]
	v_lshl_add_u32 v48, v142, 1, v245
	v_mov_b32_e32 v49, v135
	v_lshl_add_u64 v[46:47], v[46:47], 0, v[48:49]
	v_cvt_pk_bf16_f32 v48, v42, v43
	v_cvt_pk_bf16_f32 v49, v44, v45
	s_nop 1
	v_mov_b32_dpp v246, v48 quad_perm:[1,0,3,2] row_mask:0xf bank_mask:0xf
	v_mov_b32_dpp v247, v49 quad_perm:[1,0,3,2] row_mask:0xf bank_mask:0xf
	v_perm_b32 v246, v246, v48, v248
	v_perm_b32 v247, v247, v49, v248
	s_nop 1
	v_mov_b32_dpp v250, v246 quad_perm:[2,3,0,1] row_mask:0xf bank_mask:0xf
	v_mov_b32_dpp v251, v247 quad_perm:[2,3,0,1] row_mask:0xf bank_mask:0xf
	v_cndmask_b32_e64 v252, v246, v251, s[98:99]
	v_cndmask_b32_e64 v253, v250, v247, s[98:99]
	global_store_dwordx2 v[46:47], v[252:253], off

.LBB0_869:
	s_and_b64 vcc, exec, s[12:13]
	s_cbranch_vccz .LBB0_871
	s_and_b64 s[12:13], s[8:9], exec
	s_cselect_b32 s12, s89, 0xc100000
	s_add_u32 s12, s84, s12
	v_cndmask_b32_e64 v39, v53, v51, s[8:9]
	v_cndmask_b32_e64 v38, v52, v50, s[8:9]
	s_addc_u32 s13, s85, 0
	v_cndmask_b32_e64 v41, v61, v45, s[8:9]
	v_cndmask_b32_e64 v40, v60, v44, s[8:9]
	v_lshl_add_u64 v[38:39], s[12:13], 0, v[38:39]
	v_lshlrev_b32_e32 v44, 2, v177
	v_mov_b32_e32 v45, v135
	v_lshl_add_u64 v[38:39], v[38:39], 0, v[44:45]
	s_and_b64 s[12:13], s[8:9], exec
	v_and_or_b32 v40, v124, s94, v40
	global_store_dwordx4 v[38:39], v[34:37], off offset:576 nt
	s_cselect_b32 s13, s28, s57
	s_cselect_b32 s12, s3, s56
	v_lshlrev_b64 v[38:39], 7, v[40:41]
	v_lshl_add_u64 v[38:39], s[12:13], 0, v[38:39]
	v_lshl_add_u32 v40, v142, 1, v245
	v_mov_b32_e32 v41, v135
	v_lshl_add_u64 v[38:39], v[38:39], 0, v[40:41]
	v_cvt_pk_bf16_f32 v40, v34, v35
	v_cvt_pk_bf16_f32 v41, v36, v37
	s_nop 1
	v_mov_b32_dpp v246, v40 quad_perm:[1,0,3,2] row_mask:0xf bank_mask:0xf
	v_mov_b32_dpp v247, v41 quad_perm:[1,0,3,2] row_mask:0xf bank_mask:0xf
	v_perm_b32 v246, v246, v40, v248
	v_perm_b32 v247, v247, v41, v248
	s_nop 1
	v_mov_b32_dpp v250, v246 quad_perm:[2,3,0,1] row_mask:0xf bank_mask:0xf
	v_mov_b32_dpp v251, v247 quad_perm:[2,3,0,1] row_mask:0xf bank_mask:0xf
	v_cndmask_b32_e64 v252, v246, v251, s[98:99]
	v_cndmask_b32_e64 v253, v250, v247, s[98:99]
	global_store_dwordx2 v[38:39], v[252:253], off

.LBB0_888:
	s_and_b64 vcc, exec, s[12:13]
	s_cbranch_vccz .LBB0_890
	s_and_b64 s[12:13], s[8:9], exec
	s_cselect_b32 s12, s89, 0xc100000
	v_mov_b32_e32 v32, s93
	s_add_u32 s12, s84, s12
	v_cndmask_b32_e64 v31, v37, v35, s[8:9]
	v_cndmask_b32_e64 v30, v36, v34, s[8:9]
	v_cndmask_b32_e64 v33, v32, v45, s[8:9]
	v_mov_b32_e32 v32, s67
	s_addc_u32 s13, s85, 0
	v_cndmask_b32_e64 v32, v32, v44, s[8:9]
	v_lshl_add_u64 v[30:31], s[12:13], 0, v[30:31]
	v_lshlrev_b32_e32 v44, 2, v177
	v_mov_b32_e32 v45, v135
	v_lshl_add_u64 v[30:31], v[30:31], 0, v[44:45]
	s_and_b64 s[12:13], s[8:9], exec
	v_and_or_b32 v32, v178, s94, v32
	global_store_dwordx4 v[30:31], v[26:29], off offset:64 nt
	s_cselect_b32 s13, s28, s57
	s_cselect_b32 s12, s3, s56
	v_lshlrev_b64 v[30:31], 7, v[32:33]
	v_cndmask_b32_e64 v32, v146, v138, s[8:9]
	v_lshl_add_u64 v[30:31], s[12:13], 0, v[30:31]
	v_lshl_add_u32 v32, v32, 1, v245
	v_mov_b32_e32 v33, v135
	v_lshl_add_u64 v[30:31], v[30:31], 0, v[32:33]
	v_cvt_pk_bf16_f32 v32, v26, v27
	v_cvt_pk_bf16_f32 v33, v28, v29
	s_nop 1
	v_mov_b32_dpp v246, v32 quad_perm:[1,0,3,2] row_mask:0xf bank_mask:0xf
	v_mov_b32_dpp v247, v33 quad_perm:[1,0,3,2] row_mask:0xf bank_mask:0xf
	v_perm_b32 v246, v246, v32, v248
	v_perm_b32 v247, v247, v33, v248
	s_nop 1
	v_mov_b32_dpp v250, v246 quad_perm:[2,3,0,1] row_mask:0xf bank_mask:0xf
	v_mov_b32_dpp v251, v247 quad_perm:[2,3,0,1] row_mask:0xf bank_mask:0xf
	v_cndmask_b32_e64 v252, v246, v251, s[98:99]
	v_cndmask_b32_e64 v253, v250, v247, s[98:99]
	global_store_dwordx2 v[30:31], v[252:253], off

.LBB0_907:
	s_and_b64 vcc, exec, s[12:13]
	s_cbranch_vccz .LBB0_909
	s_and_b64 s[12:13], s[8:9], exec
	s_cselect_b32 s12, s89, 0xc100000
	s_add_u32 s12, s84, s12
	v_cndmask_b32_e64 v23, v37, v35, s[8:9]
	v_cndmask_b32_e64 v22, v36, v34, s[8:9]
	s_addc_u32 s13, s85, 0
	v_cndmask_b32_e64 v25, v61, v29, s[8:9]
	v_cndmask_b32_e64 v24, v60, v28, s[8:9]
	v_lshl_add_u64 v[22:23], s[12:13], 0, v[22:23]
	v_lshlrev_b32_e32 v28, 2, v177
	v_mov_b32_e32 v29, v135
	v_lshl_add_u64 v[22:23], v[22:23], 0, v[28:29]
	s_and_b64 s[12:13], s[8:9], exec
	v_and_or_b32 v24, v124, s94, v24
	global_store_dwordx4 v[22:23], v[18:21], off offset:576 nt
	s_cselect_b32 s13, s28, s57
	s_cselect_b32 s12, s3, s56
	v_lshlrev_b64 v[22:23], 7, v[24:25]
	v_cndmask_b32_e64 v24, v146, v138, s[8:9]
	v_lshl_add_u64 v[22:23], s[12:13], 0, v[22:23]
	v_lshl_add_u32 v24, v24, 1, v245
	v_mov_b32_e32 v25, v135
	v_lshl_add_u64 v[22:23], v[22:23], 0, v[24:25]
	v_cvt_pk_bf16_f32 v24, v18, v19
	v_cvt_pk_bf16_f32 v25, v20, v21
	s_nop 1
	v_mov_b32_dpp v246, v24 quad_perm:[1,0,3,2] row_mask:0xf bank_mask:0xf
	v_mov_b32_dpp v247, v25 quad_perm:[1,0,3,2] row_mask:0xf bank_mask:0xf
	v_perm_b32 v246, v246, v24, v248
	v_perm_b32 v247, v247, v25, v248
	s_nop 1
	v_mov_b32_dpp v250, v246 quad_perm:[2,3,0,1] row_mask:0xf bank_mask:0xf
	v_mov_b32_dpp v251, v247 quad_perm:[2,3,0,1] row_mask:0xf bank_mask:0xf
	v_cndmask_b32_e64 v252, v246, v251, s[98:99]
	v_cndmask_b32_e64 v253, v250, v247, s[98:99]
	global_store_dwordx2 v[22:23], v[252:253], off

.LBB0_926:
	s_and_b64 vcc, exec, s[12:13]
	s_cbranch_vccz .LBB0_928
	s_and_b64 s[12:13], s[8:9], exec
	s_cselect_b32 s12, s89, 0xc100000
	v_mov_b32_e32 v16, s93
	s_add_u32 s12, s84, s12
	v_cndmask_b32_e64 v15, v21, v19, s[8:9]
	v_cndmask_b32_e64 v14, v20, v18, s[8:9]
	v_cndmask_b32_e64 v17, v16, v29, s[8:9]
	v_mov_b32_e32 v16, s67
	s_addc_u32 s13, s85, 0
	v_cndmask_b32_e64 v16, v16, v28, s[8:9]
	v_lshl_add_u64 v[14:15], s[12:13], 0, v[14:15]
	v_lshlrev_b32_e32 v28, 2, v177
	v_mov_b32_e32 v29, v135
	v_lshl_add_u64 v[14:15], v[14:15], 0, v[28:29]
	s_and_b64 s[12:13], s[8:9], exec
	v_and_or_b32 v16, v178, s94, v16
	global_store_dwordx4 v[14:15], v[10:13], off offset:64 nt
	s_cselect_b32 s13, s28, s57
	s_cselect_b32 s12, s3, s56
	v_lshlrev_b64 v[14:15], 7, v[16:17]
	v_cndmask_b32_e64 v16, v148, v150, s[8:9]
	v_lshl_add_u64 v[14:15], s[12:13], 0, v[14:15]
	v_lshl_add_u32 v16, v16, 1, v245
	v_mov_b32_e32 v17, v135
	v_lshl_add_u64 v[14:15], v[14:15], 0, v[16:17]
	v_cvt_pk_bf16_f32 v16, v10, v11
	v_cvt_pk_bf16_f32 v17, v12, v13
	s_nop 1
	v_mov_b32_dpp v246, v16 quad_perm:[1,0,3,2] row_mask:0xf bank_mask:0xf
	v_mov_b32_dpp v247, v17 quad_perm:[1,0,3,2] row_mask:0xf bank_mask:0xf
	v_perm_b32 v246, v246, v16, v248
	v_perm_b32 v247, v247, v17, v248
	s_nop 1
	v_mov_b32_dpp v250, v246 quad_perm:[2,3,0,1] row_mask:0xf bank_mask:0xf
	v_mov_b32_dpp v251, v247 quad_perm:[2,3,0,1] row_mask:0xf bank_mask:0xf
	v_cndmask_b32_e64 v252, v246, v251, s[98:99]
	v_cndmask_b32_e64 v253, v250, v247, s[98:99]
	global_store_dwordx2 v[14:15], v[252:253], off

.LBB0_945:
	s_and_b64 vcc, exec, s[12:13]
	s_cbranch_vccz .LBB0_947
	s_and_b64 s[12:13], s[8:9], exec
	s_cselect_b32 s12, s89, 0xc100000
	s_add_u32 s12, s84, s12
	v_cndmask_b32_e64 v7, v21, v19, s[8:9]
	v_cndmask_b32_e64 v6, v20, v18, s[8:9]
	s_addc_u32 s13, s85, 0
	v_cndmask_b32_e64 v9, v61, v13, s[8:9]
	v_cndmask_b32_e64 v8, v60, v12, s[8:9]
	v_lshl_add_u64 v[6:7], s[12:13], 0, v[6:7]
	v_lshlrev_b32_e32 v12, 2, v177
	v_mov_b32_e32 v13, v135
	v_lshl_add_u64 v[6:7], v[6:7], 0, v[12:13]
	s_and_b64 s[12:13], s[8:9], exec
	v_and_or_b32 v8, v124, s94, v8
	global_store_dwordx4 v[6:7], v[2:5], off offset:576 nt
	s_cselect_b32 s13, s28, s57
	s_cselect_b32 s12, s3, s56
	v_lshlrev_b64 v[6:7], 7, v[8:9]
	v_cndmask_b32_e64 v8, v148, v150, s[8:9]
	v_lshl_add_u64 v[6:7], s[12:13], 0, v[6:7]
	v_lshl_add_u32 v8, v8, 1, v245
	v_mov_b32_e32 v9, v135
	v_lshl_add_u64 v[6:7], v[6:7], 0, v[8:9]
	v_cvt_pk_bf16_f32 v8, v2, v3
	v_cvt_pk_bf16_f32 v9, v4, v5
	s_nop 1
	v_mov_b32_dpp v246, v8 quad_perm:[1,0,3,2] row_mask:0xf bank_mask:0xf
	v_mov_b32_dpp v247, v9 quad_perm:[1,0,3,2] row_mask:0xf bank_mask:0xf
	v_perm_b32 v246, v246, v8, v248
	v_perm_b32 v247, v247, v9, v248
	s_nop 1
	v_mov_b32_dpp v250, v246 quad_perm:[2,3,0,1] row_mask:0xf bank_mask:0xf
	v_mov_b32_dpp v251, v247 quad_perm:[2,3,0,1] row_mask:0xf bank_mask:0xf
	v_cndmask_b32_e64 v252, v246, v251, s[98:99]
	v_cndmask_b32_e64 v253, v250, v247, s[98:99]
	global_store_dwordx2 v[6:7], v[252:253], off
